# prompt attention QK: K-row reads one step ahead of their MFMA (two alternating operand quads, lgkmcnt(1)) in the three fully serialized tiles
# speedup vs baseline: 1.0009x; 1.0009x over previous
; #define LAS __attribute__((address_space(3)))
; #define MFMA32(a, b, c) __builtin_amdgcn_mfma_f32_32x32x16_bf16((a), (b), (c), 0, 0, 0)
; __device__ __forceinline__ void attn_run(LAS unsigned char* lds, const Params& p, const bf16_t* P, bf16_t* Y, float* ssa, int l, int t0, int t1, int wave) {
;     ...
;             const bf16_t* gp = P + qrow * DPROJ + O_GA + head * 64 + 8 * h;
;             u32x4 gwv[4];
; #pragma unroll
;             for (int e = 0; e < 4; ++e) gwv[e] = *(const u32x4*)(gp + 16 * e);
;             const int T0 = c >= 2 ? 0 : 2 * (2 - c);
;             const int sl0 = (c + 1) % 3, sl1 = (c + 2) % 3, sl2 = c % 3;
;             f32x16 st[6];
; #pragma unroll
;             for (int T = 0; T < 6; ++T) {
;                 f32x16 acc;
;                 const int prow = 64 * ((T >> 1) == 0 ? sl0 : ((T >> 1) == 1 ? sl1 : sl2)) + 32 * (T & 1);
;                 if (T >= T0) {
; #pragma unroll
;                     for (int e = 0; e < 16; ++e) acc[e] = 0.f;
; #pragma unroll
;                     for (int s = 0; s < 4; ++s) { const bf16x8 a = *(const LAS bf16x8*)(KS + (prow + r) * 72 + 16 * s + 8 * h); acc = MFMA32(a, qf[s], acc); }
;                 } else {
; #pragma unroll
;                     for (int e = 0; e < 16; ++e) acc[e] = -1e30f;
;                 }
;                 st[T] = acc;
;             }
.LBB0_335:
	global_load_dwordx4 v[134:137], v[2:3], off offset:3072
	global_load_dwordx4 v[130:133], v[2:3], off offset:3104
	global_load_dwordx4 v[126:129], v[2:3], off offset:3136
	global_load_dwordx4 v[122:125], v[2:3], off offset:3168
	s_lshl_b32 s10, s23, 1
	s_sub_i32 s10, 4, s10
	s_cmp_lt_u32 s23, 2
	s_cselect_b32 s33, s10, 0
	s_add_i32 s10, s23, 1
	s_mul_i32 s11, s10, 0x56
	s_lshr_b32 s11, s11, 8
	s_add_i32 s10, s10, s11
	s_lshl_b32 s10, s10, 6
	s_and_b32 s29, s10, 0xc0
	s_cmp_eq_u32 s33, 0
	v_mov_b32_e32 v18, 0xf149f2ca
	s_cselect_b64 s[10:11], -1, 0
	s_cmp_lg_u32 s33, 0
	v_mov_b32_e32 v50, 0xf149f2ca
	v_mov_b32_e32 v51, 0xf149f2ca
	v_mov_b32_e32 v52, 0xf149f2ca
	v_mov_b32_e32 v53, 0xf149f2ca
	v_mov_b32_e32 v54, 0xf149f2ca
	v_mov_b32_e32 v55, 0xf149f2ca
	v_mov_b32_e32 v56, 0xf149f2ca
	v_mov_b32_e32 v57, 0xf149f2ca
	v_mov_b32_e32 v58, 0xf149f2ca
	v_mov_b32_e32 v59, 0xf149f2ca
	v_mov_b32_e32 v60, 0xf149f2ca
	v_mov_b32_e32 v61, 0xf149f2ca
	v_mov_b32_e32 v62, 0xf149f2ca
	v_mov_b32_e32 v63, 0xf149f2ca
	v_mov_b32_e32 v64, 0xf149f2ca
	v_mov_b32_e32 v65, 0xf149f2ca
	s_cbranch_scc1 .LBB0_337
	v_or_b32_e32 v0, s29, v155
	v_mad_u32_u24 v0, v0, s89, v166
	ds_read_b128 v[2:5], v0
	ds_read_b128 v[234:237], v0 offset:32
	s_waitcnt vmcnt(7) lgkmcnt(1)
	v_mfma_f32_32x32x16_bf16 v[50:65], v[2:5], v[66:69], 0
	ds_read_b128 v[2:5], v0 offset:64
	s_waitcnt vmcnt(6) lgkmcnt(1)
	v_mfma_f32_32x32x16_bf16 v[50:65], v[234:237], v[146:149], v[50:65]
	ds_read_b128 v[234:237], v0 offset:96
	s_waitcnt vmcnt(5) lgkmcnt(1)
	v_mfma_f32_32x32x16_bf16 v[50:65], v[2:5], v[142:145], v[50:65]
	s_waitcnt vmcnt(4) lgkmcnt(0)
	v_mfma_f32_32x32x16_bf16 v[50:65], v[234:237], v[138:141], v[50:65]
.LBB0_337:
	v_cndmask_b32_e64 v0, 0, 1, s[10:11]
	v_cmp_ne_u32_e64 s[42:43], 1, v0
	s_andn2_b64 vcc, exec, s[10:11]
	v_mov_b32_e32 v19, 0xf149f2ca
	v_mov_b32_e32 v20, 0xf149f2ca
	v_mov_b32_e32 v21, 0xf149f2ca
	v_mov_b32_e32 v22, 0xf149f2ca
	v_mov_b32_e32 v23, 0xf149f2ca
	v_mov_b32_e32 v24, 0xf149f2ca
	v_mov_b32_e32 v25, 0xf149f2ca
	v_mov_b32_e32 v26, 0xf149f2ca
	v_mov_b32_e32 v27, 0xf149f2ca
	v_mov_b32_e32 v28, 0xf149f2ca
	v_mov_b32_e32 v29, 0xf149f2ca
	v_mov_b32_e32 v30, 0xf149f2ca
	v_mov_b32_e32 v31, 0xf149f2ca
	v_mov_b32_e32 v32, 0xf149f2ca
	v_mov_b32_e32 v33, 0xf149f2ca
	s_cbranch_vccnz .LBB0_339
	v_or_b32_e32 v0, s29, v155
	v_mad_u32_u24 v0, v0, s89, v166
	ds_read_b128 v[2:5], v0 offset:4608
	ds_read_b128 v[234:237], v0 offset:4640
	s_waitcnt vmcnt(7) lgkmcnt(1)
	v_mfma_f32_32x32x16_bf16 v[18:33], v[2:5], v[66:69], 0
	ds_read_b128 v[2:5], v0 offset:4672
	s_waitcnt vmcnt(6) lgkmcnt(1)
	v_mfma_f32_32x32x16_bf16 v[18:33], v[234:237], v[146:149], v[18:33]
	ds_read_b128 v[234:237], v0 offset:4704
	s_waitcnt vmcnt(5) lgkmcnt(1)
	v_mfma_f32_32x32x16_bf16 v[18:33], v[2:5], v[142:145], v[18:33]
	s_waitcnt vmcnt(4) lgkmcnt(0)
	v_mfma_f32_32x32x16_bf16 v[18:33], v[234:237], v[138:141], v[18:33]
.LBB0_339:
	s_add_i32 s10, s23, 2
	s_mul_i32 s11, s10, 0x56
	s_bfe_u32 s11, s11, 0x80008
	s_add_i32 s10, s10, s11
	s_lshl_b32 s10, s10, 6
	s_and_b32 s26, s10, 0xc0
	s_cmp_lt_u32 s33, 3
	v_or_b32_e32 v0, s26, v155
	v_mov_b32_e32 v2, 0xf149f2ca
	s_cselect_b64 s[14:15], -1, 0
	s_cmp_gt_u32 s33, 2
	v_mad_u32_u24 v0, v0, s89, v166
	v_mov_b32_e32 v34, 0xf149f2ca
	v_mov_b32_e32 v35, 0xf149f2ca
	v_mov_b32_e32 v36, 0xf149f2ca
	v_mov_b32_e32 v37, 0xf149f2ca
	v_mov_b32_e32 v38, 0xf149f2ca
	v_mov_b32_e32 v39, 0xf149f2ca
	v_mov_b32_e32 v40, 0xf149f2ca
	v_mov_b32_e32 v41, 0xf149f2ca
	v_mov_b32_e32 v42, 0xf149f2ca
	v_mov_b32_e32 v43, 0xf149f2ca
	v_mov_b32_e32 v44, 0xf149f2ca
	v_mov_b32_e32 v45, 0xf149f2ca
	v_mov_b32_e32 v46, 0xf149f2ca
	v_mov_b32_e32 v47, 0xf149f2ca
	v_mov_b32_e32 v48, 0xf149f2ca
	v_mov_b32_e32 v49, 0xf149f2ca
	s_cbranch_scc1 .LBB0_341
	ds_read_b128 v[4:7], v0
	ds_read_b128 v[234:237], v0 offset:32
	s_waitcnt vmcnt(7) lgkmcnt(1)
	v_mfma_f32_32x32x16_bf16 v[34:49], v[4:7], v[66:69], 0
	ds_read_b128 v[4:7], v0 offset:64
	s_waitcnt vmcnt(6) lgkmcnt(1)
	v_mfma_f32_32x32x16_bf16 v[34:49], v[234:237], v[146:149], v[34:49]
	ds_read_b128 v[234:237], v0 offset:96
	s_waitcnt vmcnt(5) lgkmcnt(1)
	v_mfma_f32_32x32x16_bf16 v[34:49], v[4:7], v[142:145], v[34:49]
	s_waitcnt vmcnt(4) lgkmcnt(0)
	v_mfma_f32_32x32x16_bf16 v[34:49], v[234:237], v[138:141], v[34:49]

; #define LAS __attribute__((address_space(3)))
; #define MFMA32(a, b, c) __builtin_amdgcn_mfma_f32_32x32x16_bf16((a), (b), (c), 0, 0, 0)
; __device__ __forceinline__ void attn_run(LAS unsigned char* lds, const Params& p, const bf16_t* P, bf16_t* Y, float* ssa, int l, int t0, int t1, int wave) {
;     ...
;             const bf16_t* gp = P + qrow * DPROJ + O_GA + head * 64 + 8 * h;
;             u32x4 gwv[4];
; #pragma unroll
;             for (int e = 0; e < 4; ++e) gwv[e] = *(const u32x4*)(gp + 16 * e);
;             const int T0 = c >= 2 ? 0 : 2 * (2 - c);
;             const int sl0 = (c + 1) % 3, sl1 = (c + 2) % 3, sl2 = c % 3;
;             f32x16 st[6];
; #pragma unroll
;             for (int T = 0; T < 6; ++T) {
;                 f32x16 acc;
;                 const int prow = 64 * ((T >> 1) == 0 ? sl0 : ((T >> 1) == 1 ? sl1 : sl2)) + 32 * (T & 1);
;                 if (T >= T0) {
; #pragma unroll
;                     for (int e = 0; e < 16; ++e) acc[e] = 0.f;
; #pragma unroll
;                     for (int s = 0; s < 4; ++s) { const bf16x8 a = *(const LAS bf16x8*)(KS + (prow + r) * 72 + 16 * s + 8 * h); acc = MFMA32(a, qf[s], acc); }
;                 } else {
; #pragma unroll
;                     for (int e = 0; e < 16; ++e) acc[e] = -1e30f;
;                 }
;                 st[T] = acc;
;             }
.LBB0_420:
	global_load_dwordx4 v[134:137], v[2:3], off offset:3072
	global_load_dwordx4 v[130:133], v[2:3], off offset:3104
	global_load_dwordx4 v[126:129], v[2:3], off offset:3136
	global_load_dwordx4 v[122:125], v[2:3], off offset:3168
	s_lshl_b32 s10, s22, 1
	s_sub_i32 s10, 4, s10
	s_cmp_lt_u32 s22, 2
	s_cselect_b32 s29, s10, 0
	s_add_i32 s10, s22, 1
	s_mul_i32 s11, s10, 0x56
	s_lshr_b32 s11, s11, 8
	s_add_i32 s10, s10, s11
	s_lshl_b32 s10, s10, 6
	s_and_b32 s26, s10, 0xc0
	s_cmp_eq_u32 s29, 0
	v_mov_b32_e32 v18, 0xf149f2ca
	s_cselect_b64 s[10:11], -1, 0
	s_cmp_lg_u32 s29, 0
	v_mov_b32_e32 v50, 0xf149f2ca
	v_mov_b32_e32 v51, 0xf149f2ca
	v_mov_b32_e32 v52, 0xf149f2ca
	v_mov_b32_e32 v53, 0xf149f2ca
	v_mov_b32_e32 v54, 0xf149f2ca
	v_mov_b32_e32 v55, 0xf149f2ca
	v_mov_b32_e32 v56, 0xf149f2ca
	v_mov_b32_e32 v57, 0xf149f2ca
	v_mov_b32_e32 v58, 0xf149f2ca
	v_mov_b32_e32 v59, 0xf149f2ca
	v_mov_b32_e32 v60, 0xf149f2ca
	v_mov_b32_e32 v61, 0xf149f2ca
	v_mov_b32_e32 v62, 0xf149f2ca
	v_mov_b32_e32 v63, 0xf149f2ca
	v_mov_b32_e32 v64, 0xf149f2ca
	v_mov_b32_e32 v65, 0xf149f2ca
	s_cbranch_scc1 .LBB0_422
	v_or_b32_e32 v0, s26, v155
	v_mad_u32_u24 v0, v0, s89, v166
	ds_read_b128 v[2:5], v0
	ds_read_b128 v[234:237], v0 offset:32
	s_waitcnt vmcnt(7) lgkmcnt(1)
	v_mfma_f32_32x32x16_bf16 v[50:65], v[2:5], v[66:69], 0
	ds_read_b128 v[2:5], v0 offset:64
	s_waitcnt vmcnt(6) lgkmcnt(1)
	v_mfma_f32_32x32x16_bf16 v[50:65], v[234:237], v[146:149], v[50:65]
	ds_read_b128 v[234:237], v0 offset:96
	s_waitcnt vmcnt(5) lgkmcnt(1)
	v_mfma_f32_32x32x16_bf16 v[50:65], v[2:5], v[142:145], v[50:65]
	s_waitcnt vmcnt(4) lgkmcnt(0)
	v_mfma_f32_32x32x16_bf16 v[50:65], v[234:237], v[138:141], v[50:65]
.LBB0_422:
	v_cndmask_b32_e64 v0, 0, 1, s[10:11]
	v_cmp_ne_u32_e64 s[42:43], 1, v0
	s_andn2_b64 vcc, exec, s[10:11]
	v_mov_b32_e32 v19, 0xf149f2ca
	v_mov_b32_e32 v20, 0xf149f2ca
	v_mov_b32_e32 v21, 0xf149f2ca
	v_mov_b32_e32 v22, 0xf149f2ca
	v_mov_b32_e32 v23, 0xf149f2ca
	v_mov_b32_e32 v24, 0xf149f2ca
	v_mov_b32_e32 v25, 0xf149f2ca
	v_mov_b32_e32 v26, 0xf149f2ca
	v_mov_b32_e32 v27, 0xf149f2ca
	v_mov_b32_e32 v28, 0xf149f2ca
	v_mov_b32_e32 v29, 0xf149f2ca
	v_mov_b32_e32 v30, 0xf149f2ca
	v_mov_b32_e32 v31, 0xf149f2ca
	v_mov_b32_e32 v32, 0xf149f2ca
	v_mov_b32_e32 v33, 0xf149f2ca
	s_cbranch_vccnz .LBB0_424
	v_or_b32_e32 v0, s26, v155
	v_mad_u32_u24 v0, v0, s89, v166
	ds_read_b128 v[2:5], v0 offset:4608
	ds_read_b128 v[234:237], v0 offset:4640
	s_waitcnt vmcnt(7) lgkmcnt(1)
	v_mfma_f32_32x32x16_bf16 v[18:33], v[2:5], v[66:69], 0
	ds_read_b128 v[2:5], v0 offset:4672
	s_waitcnt vmcnt(6) lgkmcnt(1)
	v_mfma_f32_32x32x16_bf16 v[18:33], v[234:237], v[146:149], v[18:33]
	ds_read_b128 v[234:237], v0 offset:4704
	s_waitcnt vmcnt(5) lgkmcnt(1)
	v_mfma_f32_32x32x16_bf16 v[18:33], v[2:5], v[142:145], v[18:33]
	s_waitcnt vmcnt(4) lgkmcnt(0)
	v_mfma_f32_32x32x16_bf16 v[18:33], v[234:237], v[138:141], v[18:33]
.LBB0_424:
	s_add_i32 s10, s22, 2
	s_mul_i32 s11, s10, 0x56
	s_bfe_u32 s11, s11, 0x80008
	s_add_i32 s10, s10, s11
	s_lshl_b32 s10, s10, 6
	s_and_b32 s25, s10, 0xc0
	s_cmp_lt_u32 s29, 3
	v_or_b32_e32 v0, s25, v155
	v_mov_b32_e32 v2, 0xf149f2ca
	s_cselect_b64 s[14:15], -1, 0
	s_cmp_gt_u32 s29, 2
	v_mad_u32_u24 v0, v0, s89, v166
	v_mov_b32_e32 v34, 0xf149f2ca
	v_mov_b32_e32 v35, 0xf149f2ca
	v_mov_b32_e32 v36, 0xf149f2ca
	v_mov_b32_e32 v37, 0xf149f2ca
	v_mov_b32_e32 v38, 0xf149f2ca
	v_mov_b32_e32 v39, 0xf149f2ca
	v_mov_b32_e32 v40, 0xf149f2ca
	v_mov_b32_e32 v41, 0xf149f2ca
	v_mov_b32_e32 v42, 0xf149f2ca
	v_mov_b32_e32 v43, 0xf149f2ca
	v_mov_b32_e32 v44, 0xf149f2ca
	v_mov_b32_e32 v45, 0xf149f2ca
	v_mov_b32_e32 v46, 0xf149f2ca
	v_mov_b32_e32 v47, 0xf149f2ca
	v_mov_b32_e32 v48, 0xf149f2ca
	v_mov_b32_e32 v49, 0xf149f2ca
	s_cbranch_scc1 .LBB0_426
	ds_read_b128 v[4:7], v0
	ds_read_b128 v[234:237], v0 offset:32
	s_waitcnt vmcnt(7) lgkmcnt(1)
	v_mfma_f32_32x32x16_bf16 v[34:49], v[4:7], v[66:69], 0
	ds_read_b128 v[4:7], v0 offset:64
	s_waitcnt vmcnt(6) lgkmcnt(1)
	v_mfma_f32_32x32x16_bf16 v[34:49], v[234:237], v[146:149], v[34:49]
	ds_read_b128 v[234:237], v0 offset:96
	s_waitcnt vmcnt(5) lgkmcnt(1)
	v_mfma_f32_32x32x16_bf16 v[34:49], v[4:7], v[142:145], v[34:49]
	s_waitcnt vmcnt(4) lgkmcnt(0)
	v_mfma_f32_32x32x16_bf16 v[34:49], v[234:237], v[138:141], v[34:49]
